# out-proj epilogue first half: staged-row ds_read_b128 prefetched one row-iteration ahead into alternating spare VGPR quads; stale post-DPP lgkmcnt waits removed
# baseline (speedup 1.0000x reference)
; DI float bflo(unsigned v) { return __uint_as_float(v << 16); }
; DI float bfhi(unsigned v) { return __uint_as_float(v & 0xffff0000u); }
; template <int EPI>
; DI void gemm_tile(const Params& p, int layer, int mt, int nt, u16* sm, int wv) {
;     ...
;       for (int t = 0; t < 16; ++t) {
;         const int row = (lane >> 4) + 4 * t;
;         const f32x4 a4 = *(const f32x4*)(stg + row * 68 + kc * 4);
;         const float v0 = bflo(xb[t][0]) + a4[0], v1 = bfhi(xb[t][0]) + a4[1], v2 = bflo(xb[t][1]) + a4[2], v3 = bfhi(xb[t][1]) + a4[3];
;         float sq = v0 * v0 + v1 * v1 + v2 * v2 + v3 * v3;
;         u32x2 pv = {pk2(v0, v1), pk2(v2, v3)};
;         if (has_next) *(u32x2*)(xrow + (size_t)row * DM) = pv;
;         else *(u32x2*)(x2row + (size_t)row * DM) = pv;
;         sq += shx(sq, lane, 1); sq += shx(sq, lane, 2); sq += shx(sq, lane, 4); sq += shx(sq, lane, 8);
;         if (kc == 0) atomicAdd(ssn + mrow0 + row, sq);
;       }
.LBB0_403:
	v_and_b32_e32 v66, 63, v185
	v_lshlrev_b32_e32 v71, 2, v66
	v_pk_mul_f32 v[66:67], v[104:105], v[104:105]
	v_pk_mul_f32 v[104:105], v[136:137], v[136:137]
	v_add_f32_e32 v66, v66, v67
	v_add_f32_e32 v66, v104, v66
	v_xor_b32_e32 v138, 4, v71
	v_add_f32_e32 v66, v105, v66
	s_nop 1
	v_mov_b32_dpp v67, v66 quad_perm:[1,0,3,2] row_mask:0xf bank_mask:0xf
	v_xor_b32_e32 v137, 8, v71
	v_xor_b32_e32 v139, 16, v71
	v_xor_b32_e32 v136, 32, v71
	v_cmp_eq_u32_e64 s[36:37], 0, v180
	v_add_f32_e32 v66, v66, v67
	s_nop 1
	v_mov_b32_dpp v67, v66 quad_perm:[2,3,0,1] row_mask:0xf bank_mask:0xf
	v_lshl_add_u64 v[104:105], v[68:69], 2, s[0:1]
	v_add_f32_e32 v66, v66, v67
	s_nop 1
	v_mov_b32_dpp v67, v66 row_half_mirror row_mask:0xf bank_mask:0xf
	v_add_f32_e32 v67, v66, v67
	s_nop 1
	v_mov_b32_dpp v71, v67 row_mirror row_mask:0xf bank_mask:0xf
	v_lshlrev_b32_e32 v66, 2, v183
	v_add_f32_e32 v146, v67, v71
	v_cmp_eq_u32_e64 s[4:5], 0, v180
	s_nop 1
	v_cndmask_b32_e64 v147, v147, v146, s[4:5]
.LBB0_405:
	v_mul_u32_u24_e32 v67, 0x110, v183
	v_add_u32_e32 v69, v67, v184
	ds_read_b128 v[156:159], v69 offset:1088
	v_lshlrev_b32_e32 v144, 16, v132
	v_and_b32_e32 v145, 0xffff0000, v132
	v_lshlrev_b32_e32 v132, 16, v133
	v_and_b32_e32 v133, 0xffff0000, v133
	s_waitcnt lgkmcnt(0)
	ds_read_b128 v[160:163], v69 offset:2176
	v_pk_add_f32 v[140:141], v[156:157], v[144:145]
	v_pk_add_f32 v[142:143], v[158:159], v[132:133]
	v_pk_mul_f32 v[132:133], v[140:141], v[140:141]
	v_pk_mul_f32 v[144:145], v[142:143], v[142:143]
	v_add_f32_e32 v67, v132, v133
	v_add_f32_e32 v67, v144, v67
	v_add_f32_e32 v67, v145, v67
	s_nop 1
	v_mov_b32_dpp v71, v67 quad_perm:[1,0,3,2] row_mask:0xf bank_mask:0xf
	v_or_b32_e32 v132, 4, v183
	v_cndmask_b32_e64 v111, v135, v111, s[34:35]
	v_cndmask_b32_e64 v110, v134, v110, s[34:35]
	v_lshlrev_b32_e32 v134, 11, v132
	v_add_f32_e32 v67, v67, v71
	s_nop 1
	v_mov_b32_dpp v71, v67 quad_perm:[2,3,0,1] row_mask:0xf bank_mask:0xf
	v_mov_b32_e32 v135, v1
	v_cvt_pk_bf16_f32 v140, v140, v141
	v_cvt_pk_bf16_f32 v141, v142, v143
	v_lshl_add_u64 v[134:135], v[110:111], 0, v[134:135]
	v_add_f32_e32 v67, v67, v71
	s_nop 1
	v_mov_b32_dpp v71, v67 row_half_mirror row_mask:0xf bank_mask:0xf
	global_store_dwordx2 v[134:135], v[140:141], off
	v_add_f32_e32 v67, v67, v71
	s_nop 1
	v_mov_b32_dpp v71, v67 row_mirror row_mask:0xf bank_mask:0xf
	v_add_f32_e32 v146, v67, v71
	v_cmp_eq_u32_e64 s[4:5], 1, v180
	s_nop 1
	v_cndmask_b32_e64 v147, v147, v146, s[4:5]
.LBB0_407:
	v_lshlrev_b32_e32 v134, 16, v130
	v_and_b32_e32 v135, 0xffff0000, v130
	v_lshlrev_b32_e32 v130, 16, v131
	v_and_b32_e32 v131, 0xffff0000, v131
	s_waitcnt lgkmcnt(0)
	ds_read_b128 v[156:159], v69 offset:3264
	v_pk_add_f32 v[134:135], v[160:161], v[134:135]
	v_pk_add_f32 v[140:141], v[162:163], v[130:131]
	v_pk_mul_f32 v[130:131], v[134:135], v[134:135]
	v_pk_mul_f32 v[142:143], v[140:141], v[140:141]
	v_add_f32_e32 v67, v130, v131
	v_add_f32_e32 v67, v142, v67
	v_add_f32_e32 v67, v143, v67
	s_nop 1
	v_mov_b32_dpp v71, v67 quad_perm:[1,0,3,2] row_mask:0xf bank_mask:0xf
	v_or_b32_e32 v130, 8, v183
	v_cvt_pk_bf16_f32 v134, v134, v135
	v_cvt_pk_bf16_f32 v135, v140, v141
	v_lshlrev_b32_e32 v140, 11, v130
	v_add_f32_e32 v67, v67, v71
	s_nop 1
	v_mov_b32_dpp v71, v67 quad_perm:[2,3,0,1] row_mask:0xf bank_mask:0xf
	v_mov_b32_e32 v141, v1
	v_lshl_add_u64 v[140:141], v[110:111], 0, v[140:141]
	global_store_dwordx2 v[140:141], v[134:135], off
	v_add_f32_e32 v67, v67, v71
	s_nop 1
	v_mov_b32_dpp v71, v67 row_half_mirror row_mask:0xf bank_mask:0xf
	v_add_f32_e32 v67, v67, v71
	s_nop 1
	v_mov_b32_dpp v71, v67 row_mirror row_mask:0xf bank_mask:0xf
	v_add_f32_e32 v146, v67, v71
	v_cmp_eq_u32_e64 s[4:5], 2, v180
	s_nop 1
	v_cndmask_b32_e64 v147, v147, v146, s[4:5]
.LBB0_409:
	v_lshlrev_b32_e32 v134, 16, v128
	v_and_b32_e32 v135, 0xffff0000, v128
	v_lshlrev_b32_e32 v128, 16, v129
	v_and_b32_e32 v129, 0xffff0000, v129
	s_waitcnt lgkmcnt(0)
	ds_read_b128 v[160:163], v69 offset:4352
	v_pk_add_f32 v[134:135], v[156:157], v[134:135]
	v_pk_add_f32 v[140:141], v[158:159], v[128:129]
	v_pk_mul_f32 v[128:129], v[134:135], v[134:135]
	v_pk_mul_f32 v[142:143], v[140:141], v[140:141]
	v_add_f32_e32 v67, v128, v129
	v_add_f32_e32 v67, v142, v67
	v_add_f32_e32 v67, v143, v67
	s_nop 1
	v_mov_b32_dpp v71, v67 quad_perm:[1,0,3,2] row_mask:0xf bank_mask:0xf
	v_or_b32_e32 v128, 12, v183
	v_cvt_pk_bf16_f32 v134, v134, v135
	v_cvt_pk_bf16_f32 v135, v140, v141
	v_lshlrev_b32_e32 v140, 11, v128
	v_add_f32_e32 v67, v67, v71
	s_nop 1
	v_mov_b32_dpp v71, v67 quad_perm:[2,3,0,1] row_mask:0xf bank_mask:0xf
	v_mov_b32_e32 v141, v1
	v_lshl_add_u64 v[140:141], v[110:111], 0, v[140:141]
	global_store_dwordx2 v[140:141], v[134:135], off
	v_add_f32_e32 v67, v67, v71
	s_nop 1
	v_mov_b32_dpp v71, v67 row_half_mirror row_mask:0xf bank_mask:0xf
	v_add_f32_e32 v67, v67, v71
	s_nop 1
	v_mov_b32_dpp v71, v67 row_mirror row_mask:0xf bank_mask:0xf
	v_add_f32_e32 v146, v67, v71
	v_cmp_eq_u32_e64 s[4:5], 3, v180
	s_nop 1
	v_cndmask_b32_e64 v147, v147, v146, s[4:5]
; DI float bflo(unsigned v) { return __uint_as_float(v << 16); }
; DI float bfhi(unsigned v) { return __uint_as_float(v & 0xffff0000u); }
; template <int EPI>
; DI void gemm_tile(const Params& p, int layer, int mt, int nt, u16* sm, int wv) {
;     ...
;       for (int t = 0; t < 16; ++t) {
;         const int row = (lane >> 4) + 4 * t;
;         const f32x4 a4 = *(const f32x4*)(stg + row * 68 + kc * 4);
;         const float v0 = bflo(xb[t][0]) + a4[0], v1 = bfhi(xb[t][0]) + a4[1], v2 = bflo(xb[t][1]) + a4[2], v3 = bfhi(xb[t][1]) + a4[3];
;         float sq = v0 * v0 + v1 * v1 + v2 * v2 + v3 * v3;
;         u32x2 pv = {pk2(v0, v1), pk2(v2, v3)};
;         if (has_next) *(u32x2*)(xrow + (size_t)row * DM) = pv;
;         else *(u32x2*)(x2row + (size_t)row * DM) = pv;
;         sq += shx(sq, lane, 1); sq += shx(sq, lane, 2); sq += shx(sq, lane, 4); sq += shx(sq, lane, 8);
;         if (kc == 0) atomicAdd(ssn + mrow0 + row, sq);
;       }
.LBB0_411:
	v_lshlrev_b32_e32 v134, 16, v126
	v_and_b32_e32 v135, 0xffff0000, v126
	v_lshlrev_b32_e32 v126, 16, v127
	v_and_b32_e32 v127, 0xffff0000, v127
	s_waitcnt lgkmcnt(0)
	ds_read_b128 v[156:159], v69 offset:5440
	v_pk_add_f32 v[134:135], v[160:161], v[134:135]
	v_pk_add_f32 v[140:141], v[162:163], v[126:127]
	v_pk_mul_f32 v[126:127], v[134:135], v[134:135]
	v_pk_mul_f32 v[142:143], v[140:141], v[140:141]
	v_add_f32_e32 v67, v126, v127
	v_add_f32_e32 v67, v142, v67
	v_add_f32_e32 v67, v143, v67
	s_nop 1
	v_mov_b32_dpp v71, v67 quad_perm:[1,0,3,2] row_mask:0xf bank_mask:0xf
	v_or_b32_e32 v126, 16, v183
	v_cvt_pk_bf16_f32 v134, v134, v135
	v_cvt_pk_bf16_f32 v135, v140, v141
	v_lshlrev_b32_e32 v140, 11, v126
	v_add_f32_e32 v67, v67, v71
	s_nop 1
	v_mov_b32_dpp v71, v67 quad_perm:[2,3,0,1] row_mask:0xf bank_mask:0xf
	v_mov_b32_e32 v141, v1
	v_lshl_add_u64 v[140:141], v[110:111], 0, v[140:141]
	global_store_dwordx2 v[140:141], v[134:135], off
	v_add_f32_e32 v67, v67, v71
	s_nop 1
	v_mov_b32_dpp v71, v67 row_half_mirror row_mask:0xf bank_mask:0xf
	v_add_f32_e32 v67, v67, v71
	s_nop 1
	v_mov_b32_dpp v71, v67 row_mirror row_mask:0xf bank_mask:0xf
	v_add_f32_e32 v146, v67, v71
	v_cmp_eq_u32_e64 s[4:5], 4, v180
	s_nop 1
	v_cndmask_b32_e64 v147, v147, v146, s[4:5]
.LBB0_413:
	v_lshlrev_b32_e32 v134, 16, v124
	v_and_b32_e32 v135, 0xffff0000, v124
	v_lshlrev_b32_e32 v124, 16, v125
	v_and_b32_e32 v125, 0xffff0000, v125
	s_waitcnt lgkmcnt(0)
	ds_read_b128 v[160:163], v69 offset:6528
	v_pk_add_f32 v[134:135], v[156:157], v[134:135]
	v_pk_add_f32 v[140:141], v[158:159], v[124:125]
	v_pk_mul_f32 v[124:125], v[134:135], v[134:135]
	v_pk_mul_f32 v[142:143], v[140:141], v[140:141]
	v_add_f32_e32 v67, v124, v125
	v_add_f32_e32 v67, v142, v67
	v_add_f32_e32 v67, v143, v67
	s_nop 1
	v_mov_b32_dpp v71, v67 quad_perm:[1,0,3,2] row_mask:0xf bank_mask:0xf
	v_or_b32_e32 v124, 20, v183
	v_cvt_pk_bf16_f32 v134, v134, v135
	v_cvt_pk_bf16_f32 v135, v140, v141
	v_lshlrev_b32_e32 v140, 11, v124
	v_add_f32_e32 v67, v67, v71
	s_nop 1
	v_mov_b32_dpp v71, v67 quad_perm:[2,3,0,1] row_mask:0xf bank_mask:0xf
	v_mov_b32_e32 v141, v1
	v_lshl_add_u64 v[140:141], v[110:111], 0, v[140:141]
	global_store_dwordx2 v[140:141], v[134:135], off
	v_add_f32_e32 v67, v67, v71
	s_nop 1
	v_mov_b32_dpp v71, v67 row_half_mirror row_mask:0xf bank_mask:0xf
	v_add_f32_e32 v67, v67, v71
	s_nop 1
	v_mov_b32_dpp v71, v67 row_mirror row_mask:0xf bank_mask:0xf
	v_add_f32_e32 v146, v67, v71
	v_cmp_eq_u32_e64 s[4:5], 5, v180
	s_nop 1
	v_cndmask_b32_e64 v147, v147, v146, s[4:5]
.LBB0_415:
	v_lshlrev_b32_e32 v134, 16, v122
	v_and_b32_e32 v135, 0xffff0000, v122
	v_lshlrev_b32_e32 v122, 16, v123
	v_and_b32_e32 v123, 0xffff0000, v123
	s_waitcnt lgkmcnt(0)
	ds_read_b128 v[156:159], v69 offset:7616
	v_pk_add_f32 v[134:135], v[160:161], v[134:135]
	v_pk_add_f32 v[140:141], v[162:163], v[122:123]
	v_pk_mul_f32 v[122:123], v[134:135], v[134:135]
	v_pk_mul_f32 v[142:143], v[140:141], v[140:141]
	v_add_f32_e32 v67, v122, v123
	v_add_f32_e32 v67, v142, v67
	v_add_f32_e32 v67, v143, v67
	s_nop 1
	v_mov_b32_dpp v71, v67 quad_perm:[1,0,3,2] row_mask:0xf bank_mask:0xf
	v_or_b32_e32 v122, 24, v183
	v_cvt_pk_bf16_f32 v134, v134, v135
	v_cvt_pk_bf16_f32 v135, v140, v141
	v_lshlrev_b32_e32 v140, 11, v122
	v_add_f32_e32 v67, v67, v71
	s_nop 1
	v_mov_b32_dpp v71, v67 quad_perm:[2,3,0,1] row_mask:0xf bank_mask:0xf
	v_mov_b32_e32 v141, v1
	v_lshl_add_u64 v[140:141], v[110:111], 0, v[140:141]
	global_store_dwordx2 v[140:141], v[134:135], off
	v_add_f32_e32 v67, v67, v71
	s_nop 1
	v_mov_b32_dpp v71, v67 row_half_mirror row_mask:0xf bank_mask:0xf
	v_add_f32_e32 v67, v67, v71
	s_nop 1
	v_mov_b32_dpp v71, v67 row_mirror row_mask:0xf bank_mask:0xf
	v_add_f32_e32 v146, v67, v71
	v_cmp_eq_u32_e64 s[4:5], 6, v180
	s_nop 1
	v_cndmask_b32_e64 v147, v147, v146, s[4:5]
.LBB0_417:
	v_lshlrev_b32_e32 v134, 16, v120
	v_and_b32_e32 v135, 0xffff0000, v120
	v_lshlrev_b32_e32 v120, 16, v121
	v_and_b32_e32 v121, 0xffff0000, v121
	s_waitcnt lgkmcnt(0)
	ds_read_b128 v[160:163], v69 offset:8704
	v_pk_add_f32 v[134:135], v[156:157], v[134:135]
	v_pk_add_f32 v[140:141], v[158:159], v[120:121]
	v_pk_mul_f32 v[120:121], v[134:135], v[134:135]
	v_pk_mul_f32 v[142:143], v[140:141], v[140:141]
	v_add_f32_e32 v67, v120, v121
	v_add_f32_e32 v67, v142, v67
	v_add_f32_e32 v67, v143, v67
	s_nop 1
	v_mov_b32_dpp v71, v67 quad_perm:[1,0,3,2] row_mask:0xf bank_mask:0xf
	v_or_b32_e32 v120, 28, v183
	v_cvt_pk_bf16_f32 v134, v134, v135
	v_cvt_pk_bf16_f32 v135, v140, v141
	v_lshlrev_b32_e32 v140, 11, v120
	v_add_f32_e32 v67, v67, v71
	s_nop 1
	v_mov_b32_dpp v71, v67 quad_perm:[2,3,0,1] row_mask:0xf bank_mask:0xf
	v_mov_b32_e32 v141, v1
	v_lshl_add_u64 v[140:141], v[110:111], 0, v[140:141]
	global_store_dwordx2 v[140:141], v[134:135], off
	v_add_f32_e32 v67, v67, v71
	s_nop 1
	v_mov_b32_dpp v71, v67 row_half_mirror row_mask:0xf bank_mask:0xf
	v_add_f32_e32 v67, v67, v71
	s_nop 1
	v_mov_b32_dpp v71, v67 row_mirror row_mask:0xf bank_mask:0xf
	v_add_f32_e32 v146, v67, v71
	v_cmp_eq_u32_e64 s[4:5], 7, v180
	s_nop 1
	v_cndmask_b32_e64 v147, v147, v146, s[4:5]
; DI float bflo(unsigned v) { return __uint_as_float(v << 16); }
; DI float bfhi(unsigned v) { return __uint_as_float(v & 0xffff0000u); }
; template <int EPI>
; DI void gemm_tile(const Params& p, int layer, int mt, int nt, u16* sm, int wv) {
;     ...
;       for (int t = 0; t < 16; ++t) {
;         const int row = (lane >> 4) + 4 * t;
;         const f32x4 a4 = *(const f32x4*)(stg + row * 68 + kc * 4);
;         const float v0 = bflo(xb[t][0]) + a4[0], v1 = bfhi(xb[t][0]) + a4[1], v2 = bflo(xb[t][1]) + a4[2], v3 = bfhi(xb[t][1]) + a4[3];
;         float sq = v0 * v0 + v1 * v1 + v2 * v2 + v3 * v3;
;         u32x2 pv = {pk2(v0, v1), pk2(v2, v3)};
;         if (has_next) *(u32x2*)(xrow + (size_t)row * DM) = pv;
;         else *(u32x2*)(x2row + (size_t)row * DM) = pv;
;         sq += shx(sq, lane, 1); sq += shx(sq, lane, 2); sq += shx(sq, lane, 4); sq += shx(sq, lane, 8);
;         if (kc == 0) atomicAdd(ssn + mrow0 + row, sq);
;       }
.LBB0_419:
	v_lshlrev_b32_e32 v134, 16, v118
	v_and_b32_e32 v135, 0xffff0000, v118
	v_lshlrev_b32_e32 v118, 16, v119
	v_and_b32_e32 v119, 0xffff0000, v119
	s_waitcnt lgkmcnt(0)
	ds_read_b128 v[156:159], v69 offset:9792
	v_pk_add_f32 v[134:135], v[160:161], v[134:135]
	v_pk_add_f32 v[140:141], v[162:163], v[118:119]
	v_pk_mul_f32 v[118:119], v[134:135], v[134:135]
	v_pk_mul_f32 v[142:143], v[140:141], v[140:141]
	v_add_f32_e32 v67, v118, v119
	v_add_f32_e32 v67, v142, v67
	v_add_f32_e32 v67, v143, v67
	s_nop 1
	v_mov_b32_dpp v71, v67 quad_perm:[1,0,3,2] row_mask:0xf bank_mask:0xf
	v_or_b32_e32 v118, 32, v183
	v_cvt_pk_bf16_f32 v134, v134, v135
	v_cvt_pk_bf16_f32 v135, v140, v141
	v_lshlrev_b32_e32 v140, 11, v118
	v_add_f32_e32 v67, v67, v71
	s_nop 1
	v_mov_b32_dpp v71, v67 quad_perm:[2,3,0,1] row_mask:0xf bank_mask:0xf
	v_mov_b32_e32 v141, v1
	v_lshl_add_u64 v[140:141], v[110:111], 0, v[140:141]
	global_store_dwordx2 v[140:141], v[134:135], off
	v_add_f32_e32 v67, v67, v71
	s_nop 1
	v_mov_b32_dpp v71, v67 row_half_mirror row_mask:0xf bank_mask:0xf
	v_add_f32_e32 v67, v67, v71
	s_nop 1
	v_mov_b32_dpp v71, v67 row_mirror row_mask:0xf bank_mask:0xf
	v_add_f32_e32 v146, v67, v71
	v_cmp_eq_u32_e64 s[4:5], 8, v180
	s_nop 1
	v_cndmask_b32_e64 v147, v147, v146, s[4:5]
.LBB0_421:
	v_lshlrev_b32_e32 v134, 16, v116
	v_and_b32_e32 v135, 0xffff0000, v116
	v_lshlrev_b32_e32 v116, 16, v117
	v_and_b32_e32 v117, 0xffff0000, v117
	s_waitcnt lgkmcnt(0)
	ds_read_b128 v[160:163], v69 offset:10880
	v_pk_add_f32 v[134:135], v[156:157], v[134:135]
	v_pk_add_f32 v[140:141], v[158:159], v[116:117]
	v_pk_mul_f32 v[116:117], v[134:135], v[134:135]
	v_pk_mul_f32 v[142:143], v[140:141], v[140:141]
	v_add_f32_e32 v67, v116, v117
	v_add_f32_e32 v67, v142, v67
	v_add_f32_e32 v67, v143, v67
	s_nop 1
	v_mov_b32_dpp v71, v67 quad_perm:[1,0,3,2] row_mask:0xf bank_mask:0xf
	v_or_b32_e32 v116, 36, v183
	v_cvt_pk_bf16_f32 v134, v134, v135
	v_cvt_pk_bf16_f32 v135, v140, v141
	v_lshlrev_b32_e32 v140, 11, v116
	v_add_f32_e32 v67, v67, v71
	s_nop 1
	v_mov_b32_dpp v71, v67 quad_perm:[2,3,0,1] row_mask:0xf bank_mask:0xf
	v_mov_b32_e32 v141, v1
	v_lshl_add_u64 v[140:141], v[110:111], 0, v[140:141]
	global_store_dwordx2 v[140:141], v[134:135], off
	v_add_f32_e32 v67, v67, v71
	s_nop 1
	v_mov_b32_dpp v71, v67 row_half_mirror row_mask:0xf bank_mask:0xf
	v_add_f32_e32 v67, v67, v71
	s_nop 1
	v_mov_b32_dpp v71, v67 row_mirror row_mask:0xf bank_mask:0xf
	v_add_f32_e32 v146, v67, v71
	v_cmp_eq_u32_e64 s[4:5], 9, v180
	s_nop 1
	v_cndmask_b32_e64 v147, v147, v146, s[4:5]
.LBB0_423:
	v_lshlrev_b32_e32 v134, 16, v114
	v_and_b32_e32 v135, 0xffff0000, v114
	v_lshlrev_b32_e32 v114, 16, v115
	v_and_b32_e32 v115, 0xffff0000, v115
	s_waitcnt lgkmcnt(0)
	ds_read_b128 v[156:159], v69 offset:11968
	v_pk_add_f32 v[134:135], v[160:161], v[134:135]
	v_pk_add_f32 v[140:141], v[162:163], v[114:115]
	v_pk_mul_f32 v[114:115], v[134:135], v[134:135]
	v_pk_mul_f32 v[142:143], v[140:141], v[140:141]
	v_add_f32_e32 v67, v114, v115
	v_add_f32_e32 v67, v142, v67
	v_add_f32_e32 v67, v143, v67
	s_nop 1
	v_mov_b32_dpp v71, v67 quad_perm:[1,0,3,2] row_mask:0xf bank_mask:0xf
	v_or_b32_e32 v114, 40, v183
	v_cvt_pk_bf16_f32 v134, v134, v135
	v_cvt_pk_bf16_f32 v135, v140, v141
	v_lshlrev_b32_e32 v140, 11, v114
	v_add_f32_e32 v67, v67, v71
	s_nop 1
	v_mov_b32_dpp v71, v67 quad_perm:[2,3,0,1] row_mask:0xf bank_mask:0xf
	v_mov_b32_e32 v141, v1
	v_lshl_add_u64 v[140:141], v[110:111], 0, v[140:141]
	global_store_dwordx2 v[140:141], v[134:135], off
	v_add_f32_e32 v67, v67, v71
	s_nop 1
	v_mov_b32_dpp v71, v67 row_half_mirror row_mask:0xf bank_mask:0xf
	v_add_f32_e32 v67, v67, v71
	s_nop 1
	v_mov_b32_dpp v71, v67 row_mirror row_mask:0xf bank_mask:0xf
	v_add_f32_e32 v146, v67, v71
	v_cmp_eq_u32_e64 s[4:5], 10, v180
	s_nop 1
	v_cndmask_b32_e64 v147, v147, v146, s[4:5]
.LBB0_425:
	v_lshlrev_b32_e32 v134, 16, v112
	v_and_b32_e32 v135, 0xffff0000, v112
	v_lshlrev_b32_e32 v112, 16, v113
	v_and_b32_e32 v113, 0xffff0000, v113
	s_waitcnt lgkmcnt(0)
	ds_read_b128 v[160:163], v69 offset:13056
	v_pk_add_f32 v[134:135], v[156:157], v[134:135]
	v_pk_add_f32 v[140:141], v[158:159], v[112:113]
	v_pk_mul_f32 v[112:113], v[134:135], v[134:135]
	v_pk_mul_f32 v[142:143], v[140:141], v[140:141]
	v_add_f32_e32 v67, v112, v113
	v_add_f32_e32 v67, v142, v67
	v_add_f32_e32 v67, v143, v67
	s_nop 1
	v_mov_b32_dpp v71, v67 quad_perm:[1,0,3,2] row_mask:0xf bank_mask:0xf
	v_or_b32_e32 v112, 44, v183
	v_cvt_pk_bf16_f32 v134, v134, v135
	v_cvt_pk_bf16_f32 v135, v140, v141
	v_lshlrev_b32_e32 v140, 11, v112
	v_add_f32_e32 v67, v67, v71
	s_nop 1
	v_mov_b32_dpp v71, v67 quad_perm:[2,3,0,1] row_mask:0xf bank_mask:0xf
	v_mov_b32_e32 v141, v1
	v_lshl_add_u64 v[140:141], v[110:111], 0, v[140:141]
	global_store_dwordx2 v[140:141], v[134:135], off
	v_add_f32_e32 v67, v67, v71
	s_nop 1
	v_mov_b32_dpp v71, v67 row_half_mirror row_mask:0xf bank_mask:0xf
	v_add_f32_e32 v67, v67, v71
	s_nop 1
	v_mov_b32_dpp v71, v67 row_mirror row_mask:0xf bank_mask:0xf
	v_add_f32_e32 v146, v67, v71
	v_cmp_eq_u32_e64 s[4:5], 11, v180
	s_nop 1
	v_cndmask_b32_e64 v147, v147, v146, s[4:5]
; DI float bflo(unsigned v) { return __uint_as_float(v << 16); }
; DI float bfhi(unsigned v) { return __uint_as_float(v & 0xffff0000u); }
; template <int EPI>
; DI void gemm_tile(const Params& p, int layer, int mt, int nt, u16* sm, int wv) {
;     ...
;       for (int t = 0; t < 16; ++t) {
;         const int row = (lane >> 4) + 4 * t;
;         const f32x4 a4 = *(const f32x4*)(stg + row * 68 + kc * 4);
;         const float v0 = bflo(xb[t][0]) + a4[0], v1 = bfhi(xb[t][0]) + a4[1], v2 = bflo(xb[t][1]) + a4[2], v3 = bfhi(xb[t][1]) + a4[3];
;         float sq = v0 * v0 + v1 * v1 + v2 * v2 + v3 * v3;
;         u32x2 pv = {pk2(v0, v1), pk2(v2, v3)};
;         if (has_next) *(u32x2*)(xrow + (size_t)row * DM) = pv;
;         else *(u32x2*)(x2row + (size_t)row * DM) = pv;
;         sq += shx(sq, lane, 1); sq += shx(sq, lane, 2); sq += shx(sq, lane, 4); sq += shx(sq, lane, 8);
;         if (kc == 0) atomicAdd(ssn + mrow0 + row, sq);
;       }
.LBB0_427:
	v_lshlrev_b32_e32 v134, 16, v108
	v_and_b32_e32 v135, 0xffff0000, v108
	v_lshlrev_b32_e32 v108, 16, v109
	v_and_b32_e32 v109, 0xffff0000, v109
	s_waitcnt lgkmcnt(0)
	ds_read_b128 v[156:159], v69 offset:14144
	v_pk_add_f32 v[134:135], v[160:161], v[134:135]
	v_pk_add_f32 v[140:141], v[162:163], v[108:109]
	v_pk_mul_f32 v[108:109], v[134:135], v[134:135]
	v_pk_mul_f32 v[142:143], v[140:141], v[140:141]
	v_add_f32_e32 v67, v108, v109
	v_add_f32_e32 v67, v142, v67
	v_add_f32_e32 v67, v143, v67
	s_nop 1
	v_mov_b32_dpp v71, v67 quad_perm:[1,0,3,2] row_mask:0xf bank_mask:0xf
	v_or_b32_e32 v108, 48, v183
	v_cvt_pk_bf16_f32 v134, v134, v135
	v_cvt_pk_bf16_f32 v135, v140, v141
	v_lshlrev_b32_e32 v140, 11, v108
	v_add_f32_e32 v67, v67, v71
	s_nop 1
	v_mov_b32_dpp v71, v67 quad_perm:[2,3,0,1] row_mask:0xf bank_mask:0xf
	v_mov_b32_e32 v141, v1
	v_lshl_add_u64 v[140:141], v[110:111], 0, v[140:141]
	global_store_dwordx2 v[140:141], v[134:135], off
	v_add_f32_e32 v67, v67, v71
	s_nop 1
	v_mov_b32_dpp v71, v67 row_half_mirror row_mask:0xf bank_mask:0xf
	v_add_f32_e32 v67, v67, v71
	s_nop 1
	v_mov_b32_dpp v71, v67 row_mirror row_mask:0xf bank_mask:0xf
	v_add_f32_e32 v146, v67, v71
	v_cmp_eq_u32_e64 s[4:5], 12, v180
	s_nop 1
	v_cndmask_b32_e64 v147, v147, v146, s[4:5]
.LBB0_429:
	s_waitcnt vmcnt(14)
	v_lshlrev_b32_e32 v134, 16, v106
	v_and_b32_e32 v135, 0xffff0000, v106
	v_lshlrev_b32_e32 v106, 16, v107
	v_and_b32_e32 v107, 0xffff0000, v107
	s_waitcnt lgkmcnt(0)
	ds_read_b128 v[160:163], v69 offset:15232
	v_pk_add_f32 v[134:135], v[156:157], v[134:135]
	v_pk_add_f32 v[140:141], v[158:159], v[106:107]
	v_pk_mul_f32 v[106:107], v[134:135], v[134:135]
	v_pk_mul_f32 v[142:143], v[140:141], v[140:141]
	v_add_f32_e32 v67, v106, v107
	v_add_f32_e32 v67, v142, v67
	v_add_f32_e32 v67, v143, v67
	s_nop 1
	v_mov_b32_dpp v71, v67 quad_perm:[1,0,3,2] row_mask:0xf bank_mask:0xf
	v_or_b32_e32 v106, 52, v183
	v_cvt_pk_bf16_f32 v134, v134, v135
	v_cvt_pk_bf16_f32 v135, v140, v141
	v_lshlrev_b32_e32 v140, 11, v106
	v_add_f32_e32 v67, v67, v71
	s_nop 1
	v_mov_b32_dpp v71, v67 quad_perm:[2,3,0,1] row_mask:0xf bank_mask:0xf
	v_mov_b32_e32 v141, v1
	v_lshl_add_u64 v[140:141], v[110:111], 0, v[140:141]
	global_store_dwordx2 v[140:141], v[134:135], off
	v_add_f32_e32 v67, v67, v71
	s_nop 1
	v_mov_b32_dpp v71, v67 row_half_mirror row_mask:0xf bank_mask:0xf
	v_add_f32_e32 v67, v67, v71
	s_nop 1
	v_mov_b32_dpp v71, v67 row_mirror row_mask:0xf bank_mask:0xf
	v_add_f32_e32 v146, v67, v71
	v_cmp_eq_u32_e64 s[4:5], 13, v180
	s_nop 1
	v_cndmask_b32_e64 v147, v147, v146, s[4:5]
.LBB0_431:
	s_waitcnt vmcnt(14)
	v_lshlrev_b32_e32 v134, 16, v102
	v_and_b32_e32 v135, 0xffff0000, v102
	v_lshlrev_b32_e32 v102, 16, v103
	v_and_b32_e32 v103, 0xffff0000, v103
	s_waitcnt lgkmcnt(0)
	ds_read_b128 v[156:159], v69 offset:16320
	v_pk_add_f32 v[134:135], v[160:161], v[134:135]
	v_pk_add_f32 v[140:141], v[162:163], v[102:103]
	v_pk_mul_f32 v[102:103], v[134:135], v[134:135]
	v_pk_mul_f32 v[142:143], v[140:141], v[140:141]
	v_add_f32_e32 v67, v102, v103
	v_add_f32_e32 v67, v142, v67
	v_add_f32_e32 v67, v143, v67
	s_nop 1
	v_mov_b32_dpp v71, v67 quad_perm:[1,0,3,2] row_mask:0xf bank_mask:0xf
	v_or_b32_e32 v103, 56, v183
	v_cvt_pk_bf16_f32 v134, v134, v135
	v_cvt_pk_bf16_f32 v135, v140, v141
	v_lshlrev_b32_e32 v140, 11, v103
	v_add_f32_e32 v67, v67, v71
	s_nop 1
	v_mov_b32_dpp v71, v67 quad_perm:[2,3,0,1] row_mask:0xf bank_mask:0xf
	v_mov_b32_e32 v141, v1
	v_lshl_add_u64 v[140:141], v[110:111], 0, v[140:141]
	global_store_dwordx2 v[140:141], v[134:135], off
	v_add_f32_e32 v67, v67, v71
	s_nop 1
	v_mov_b32_dpp v71, v67 row_half_mirror row_mask:0xf bank_mask:0xf
	v_add_f32_e32 v67, v67, v71
	s_nop 1
	v_mov_b32_dpp v71, v67 row_mirror row_mask:0xf bank_mask:0xf
	v_add_f32_e32 v146, v67, v71
	v_cmp_eq_u32_e64 s[4:5], 14, v180
	s_nop 1
	v_cndmask_b32_e64 v147, v147, v146, s[4:5]
.LBB0_433:
	s_waitcnt vmcnt(14)
	v_lshlrev_b32_e32 v134, 16, v100
	v_and_b32_e32 v135, 0xffff0000, v100
	v_lshlrev_b32_e32 v100, 16, v101
	v_and_b32_e32 v101, 0xffff0000, v101
	s_waitcnt lgkmcnt(0)
	v_pk_add_f32 v[134:135], v[156:157], v[134:135]
	v_pk_add_f32 v[100:101], v[158:159], v[100:101]
	v_pk_mul_f32 v[140:141], v[134:135], v[134:135]
	v_pk_mul_f32 v[142:143], v[100:101], v[100:101]
	v_add_f32_e32 v67, v140, v141
	v_add_f32_e32 v67, v142, v67
	v_add_f32_e32 v67, v143, v67
	s_nop 1
	v_mov_b32_dpp v71, v67 quad_perm:[1,0,3,2] row_mask:0xf bank_mask:0xf
	v_or_b32_e32 v102, 60, v183
	v_cvt_pk_bf16_f32 v134, v134, v135
	v_cvt_pk_bf16_f32 v135, v100, v101
	v_lshlrev_b32_e32 v100, 11, v102
	v_add_f32_e32 v67, v67, v71
	s_nop 1
	v_mov_b32_dpp v71, v67 quad_perm:[2,3,0,1] row_mask:0xf bank_mask:0xf
	v_mov_b32_e32 v101, v1
	v_lshl_add_u64 v[100:101], v[110:111], 0, v[100:101]
	global_store_dwordx2 v[100:101], v[134:135], off
	v_add_f32_e32 v67, v67, v71
	s_nop 1
	v_mov_b32_dpp v71, v67 row_half_mirror row_mask:0xf bank_mask:0xf
	v_add_f32_e32 v67, v67, v71
	s_nop 1
	v_mov_b32_dpp v71, v67 row_mirror row_mask:0xf bank_mask:0xf
	v_add_f32_e32 v146, v67, v71
	v_cmp_eq_u32_e64 s[4:5], 15, v180
	s_nop 1
	v_cndmask_b32_e64 v147, v147, v146, s[4:5]
